# v032 + non-leader blocks poll the top-level barrier generation word directly (skips the per-XCD generation hop)
# speedup vs baseline: 1.2034x; 1.0029x over previous
.LBB0_3328:
	s_or_b64 exec, exec, s[2:3]
	v_cvt_f32_u32_e32 v9, v3
	s_waitcnt vmcnt(0)
	v_readfirstlane_b32 s2, v8
	v_sub_u32_e32 v8, 0, v3
	v_rcp_iflag_f32_e32 v9, v9
	v_add_u32_e32 v10, s2, v0
	v_mul_f32_e32 v9, 0x4f7ffffe, v9
	v_cvt_u32_f32_e32 v9, v9
	v_mul_lo_u32 v0, v8, v9
	v_mul_hi_u32 v0, v9, v0
	v_add_u32_e32 v0, v9, v0
	v_mul_hi_u32 v0, v10, v0
	v_mul_lo_u32 v8, v0, v3
	v_sub_u32_e32 v8, v10, v8
	v_add_u32_e32 v9, 1, v0
	v_cmp_ge_u32_e32 vcc, v8, v3
	s_nop 1
	v_cndmask_b32_e32 v0, v0, v9, vcc
	v_sub_u32_e32 v9, v8, v3
	v_cndmask_b32_e32 v8, v8, v9, vcc
	v_add_u32_e32 v9, 1, v0
	v_cmp_ge_u32_e32 vcc, v8, v3
	v_add_u32_e32 v8, 1, v10
	s_nop 0
	v_cndmask_b32_e32 v0, v0, v9, vcc
	v_mul_lo_u32 v9, v3, v0
	v_add_u32_e32 v3, v9, v3
	v_cmp_ne_u32_e32 vcc, v8, v3
	s_and_saveexec_b64 s[2:3], vcc
	s_xor_b64 s[2:3], exec, s[2:3]
	s_cbranch_execz .LBB0_3342
	v_readlane_b32 s6, v255, 4
	v_readlane_b32 s7, v255, 5
	s_waitcnt lgkmcnt(0)
	s_nop 3
	global_load_dword v2, v1, s[6:7] sc1
	s_waitcnt vmcnt(0)
	v_cmp_eq_u32_e32 vcc, v2, v0
	s_and_saveexec_b64 s[6:7], vcc
	s_cbranch_execz .LBB0_3341
	s_mov_b32 s4, 1
	s_mov_b64 s[8:9], 0
	s_branch .LBB0_3332
